# S5 main scan item loop rewritten by hand (plain fma recurrences, batched LDS reads for the C projection, 8 interleaved GELU chains, next-item loads issued in place)
# speedup vs baseline: 1.0406x; 1.0088x over previous
.LBB0_93:
	s_or_b64 exec, exec, s[6:7]
	v_mul_f32_e32 v4, v4, v0
	v_mul_f32_e32 v7, 0x3fb8aa3b, v4
	s_mov_b32 s0, 0x3fb8aa3b
	v_fma_f32 v10, v4, s0, -v7
	v_rndne_f32_e32 v11, v7
	v_fmac_f32_e32 v10, 0x32a5705f, v4
	v_sub_f32_e32 v7, v7, v11
	v_add_f32_e32 v7, v7, v10
	v_lshlrev_b32_e32 v10, 6, v25
	s_movk_i32 s0, 0x800
	v_or3_b32 v23, v10, v34, s0
	v_cvt_i32_f32_e32 v22, v11
	global_load_dwordx4 v[10:13], v23, s[12:13] offset:16
	global_load_dwordx4 v[14:17], v23, s[12:13]
	global_load_dwordx4 v[18:21], v23, s[22:23] offset:16
	global_load_dwordx4 v[34:37], v23, s[22:23]
	v_exp_f32_e32 v7, v7
	s_mov_b32 s0, 0xc2ce8ed0
	v_cmp_ngt_f32_e32 vcc, s0, v4
	s_mov_b32 s0, 0x42b17218
	v_ldexp_f32 v7, v7, v22
	v_cndmask_b32_e32 v7, 0, v7, vcc
	v_cmp_nlt_f32_e32 vcc, s0, v4
	s_movk_i32 s0, 0x1f8
	v_ashrrev_i32_e32 v165, 6, v28
	v_cndmask_b32_e32 v4, v198, v7, vcc
	v_mul_f32_e32 v7, v6, v6
	v_fmamk_f32 v22, v7, 0xb94c1982, v194
	v_fmaak_f32 v22, v7, v22, 0xbe2aaa9d
	v_mul_f32_e32 v22, v7, v22
	v_fmac_f32_e32 v6, v6, v22
	v_fmamk_f32 v22, v7, 0x37d75334, v195
	v_fmaak_f32 v22, v7, v22, 0x3d2aabf7
	v_fmaak_f32 v22, v7, v22, 0xbf000004
	v_fma_f32 v7, v7, v22, 1.0
	v_and_b32_e32 v22, 1, v5
	v_cmp_eq_u32_e32 vcc, 0, v22
	v_lshlrev_b32_e32 v5, 30, v5
	s_nop 0
	v_cndmask_b32_e64 v6, -v6, v7, vcc
	v_bitop3_b32 v5, v5, v6, s35 bitop3:0x6c
	v_mul_f32_e32 v6, v9, v9
	v_fmamk_f32 v7, v6, 0xb94c1982, v194
	v_fmaak_f32 v7, v6, v7, 0xbe2aaa9d
	v_mul_f32_e32 v7, v6, v7
	v_fmac_f32_e32 v9, v9, v7
	v_fmamk_f32 v7, v6, 0x37d75334, v195
	v_fmaak_f32 v7, v6, v7, 0x3d2aabf7
	v_fmaak_f32 v7, v6, v7, 0xbf000004
	v_fma_f32 v6, v6, v7, 1.0
	v_and_b32_e32 v7, 1, v8
	v_cmp_eq_u32_e64 s[6:7], 0, v7
	v_lshlrev_b32_e32 v7, 30, v8
	v_cmp_class_f32_e64 vcc, v2, s0
	v_and_b32_e32 v7, 0x80000000, v7
	v_xor_b32_e32 v2, v3, v2
	v_cndmask_b32_e64 v6, v6, v9, s[6:7]
	v_xor_b32_e32 v2, v2, v7
	v_xor_b32_e32 v2, v2, v6
	v_cndmask_b32_e32 v2, v201, v2, vcc
	v_cndmask_b32_e32 v5, v201, v5, vcc
	v_mul_f32_e32 v114, v4, v2
	v_mul_f32_e32 v2, v1, v1
	v_fma_f32 v3, v4, v5, -1.0
	v_mul_f32_e32 v6, v1, v114
	v_fmac_f32_e32 v2, v0, v0
	v_fmac_f32_e32 v6, v0, v3
	v_div_scale_f32 v7, s[6:7], v2, v2, v6
	v_rcp_f32_e32 v8, v7
	v_mul_f32_e32 v1, v1, v3
	v_fma_f32 v0, v0, v114, -v1
	v_div_scale_f32 v1, s[6:7], v2, v2, v0
	v_fma_f32 v22, -v7, v8, 1.0
	v_fmac_f32_e32 v8, v22, v8
	v_div_scale_f32 v22, vcc, v6, v2, v6
	v_mul_f32_e32 v23, v22, v8
	v_fma_f32 v38, -v7, v23, v22
	v_rcp_f32_e32 v3, v1
	v_fmac_f32_e32 v23, v38, v8
	v_fma_f32 v7, -v7, v23, v22
	v_div_fmas_f32 v7, v7, v8, v23
	v_div_fixup_f32 v6, v7, v2, v6
	v_fma_f32 v7, -v1, v3, 1.0
	v_fmac_f32_e32 v3, v7, v3
	v_div_scale_f32 v7, vcc, v0, v2, v0
	v_mul_f32_e32 v8, v7, v3
	v_fma_f32 v22, -v1, v8, v7
	v_fmac_f32_e32 v8, v22, v3
	v_fma_f32 v1, -v1, v8, v7
	v_div_fmas_f32 v1, v1, v3, v8
	v_div_fixup_f32 v0, v1, v2, v0
	s_waitcnt vmcnt(2)
	v_mul_f32_e32 v1, v14, v0
	s_waitcnt vmcnt(0)
	v_fma_f32 v1, v34, v6, -v1
	v_mul_f32_e32 v2, v15, v0
	v_fma_f32 v2, v35, v6, -v2
	v_cvt_pk_bf16_f32 v72, v1, v2
	v_mul_f32_e32 v1, v16, v0
	v_fma_f32 v1, v36, v6, -v1
	v_mul_f32_e32 v2, v17, v0
	v_fma_f32 v2, v37, v6, -v2
	v_cvt_pk_bf16_f32 v73, v1, v2
	v_mul_f32_e32 v1, v10, v0
	v_fma_f32 v1, v18, v6, -v1
	v_mul_f32_e32 v2, v11, v0
	v_fma_f32 v2, v19, v6, -v2
	v_cvt_pk_bf16_f32 v74, v1, v2
	v_mul_f32_e32 v1, v12, v0
	v_fma_f32 v1, v20, v6, -v1
	v_mul_f32_e32 v2, v13, v0
	v_fma_f32 v2, v21, v6, -v2
	v_cvt_pk_bf16_f32 v75, v1, v2
	v_mul_f32_e32 v1, v34, v0
	v_fmac_f32_e32 v1, v14, v6
	v_mul_f32_e32 v2, v35, v0
	v_fmac_f32_e32 v2, v15, v6
	v_cvt_pk_bf16_f32 v76, v1, v2
	v_mul_f32_e32 v1, v36, v0
	v_fmac_f32_e32 v1, v16, v6
	v_mul_f32_e32 v2, v37, v0
	v_fmac_f32_e32 v2, v17, v6
	v_cvt_pk_bf16_f32 v77, v1, v2
	v_mul_f32_e32 v1, v18, v0
	v_fmac_f32_e32 v1, v10, v6
	v_mul_f32_e32 v2, v19, v0
	v_fmac_f32_e32 v2, v11, v6
	v_cvt_pk_bf16_f32 v78, v1, v2
	v_mul_f32_e32 v1, v20, v0
	v_mul_f32_e32 v0, v21, v0
	v_fmac_f32_e32 v1, v12, v6
	v_fmac_f32_e32 v0, v13, v6
	v_cvt_pk_bf16_f32 v79, v1, v0
	s_load_dwordx4 s[8:11], s[92:93], 0x60
	v_and_b32_e32 v0, 15, v24
	v_lshlrev_b32_e32 v1, 4, v29
	v_and_b32_e32 v9, 63, v24
	v_or_b32_e32 v3, v1, v0
	v_lshrrev_b32_e32 v2, 4, v9
	v_lshlrev_b32_e32 v158, 8, v3
	s_waitcnt lgkmcnt(0)
	v_lshl_add_u64 v[6:7], s[8:9], 0, v[158:159]
	v_lshl_add_u64 v[8:9], s[10:11], 0, v[158:159]
	v_lshlrev_b32_e32 v158, 3, v2
	v_lshl_add_u64 v[6:7], v[6:7], 0, v[158:159]
	global_load_dword v3, v[6:7], off offset:128
	global_load_dword v10, v[6:7], off
	v_lshl_add_u64 v[8:9], v[8:9], 0, v[158:159]
	s_movk_i32 s0, 0x80
	v_cmp_gt_i32_e32 vcc, s0, v165
	s_waitcnt vmcnt(0)
	v_cvt_pk_bf16_f32 v80, v10, v3
	global_load_dword v3, v[8:9], off
	global_load_dword v10, v[8:9], off offset:128
	s_waitcnt vmcnt(1)
	v_xor_b32_e32 v3, 0x80000000, v3
	s_waitcnt vmcnt(0)
	v_xor_b32_e32 v10, 0x80000000, v10
	v_cvt_pk_bf16_f32 v81, v3, v10
	global_load_dword v3, v[6:7], off offset:132
	global_load_dword v10, v[6:7], off offset:4
	s_waitcnt vmcnt(0)
	v_cvt_pk_bf16_f32 v82, v10, v3
	global_load_dword v3, v[8:9], off offset:4
	global_load_dword v10, v[8:9], off offset:132
	s_waitcnt vmcnt(1)
	v_xor_b32_e32 v3, 0x80000000, v3
	s_waitcnt vmcnt(0)
	v_xor_b32_e32 v10, 0x80000000, v10
	v_cvt_pk_bf16_f32 v83, v3, v10
	global_load_dword v3, v[6:7], off offset:160
	global_load_dword v10, v[6:7], off offset:32
	s_waitcnt vmcnt(0)
	v_cvt_pk_bf16_f32 v84, v10, v3
	global_load_dword v3, v[8:9], off offset:32
	global_load_dword v10, v[8:9], off offset:160
	s_waitcnt vmcnt(1)
	v_xor_b32_e32 v3, 0x80000000, v3
	s_waitcnt vmcnt(0)
	v_xor_b32_e32 v10, 0x80000000, v10
	v_cvt_pk_bf16_f32 v85, v3, v10
	global_load_dword v3, v[6:7], off offset:164
	global_load_dword v10, v[6:7], off offset:36
	s_waitcnt vmcnt(0)
	v_cvt_pk_bf16_f32 v86, v10, v3
	global_load_dword v3, v[8:9], off offset:36
	global_load_dword v10, v[8:9], off offset:164
	s_waitcnt vmcnt(1)
	v_xor_b32_e32 v3, 0x80000000, v3
	s_waitcnt vmcnt(0)
	v_xor_b32_e32 v10, 0x80000000, v10
	v_cvt_pk_bf16_f32 v87, v3, v10
	global_load_dword v3, v[6:7], off offset:192
	global_load_dword v10, v[6:7], off offset:64
	s_waitcnt vmcnt(0)
	v_cvt_pk_bf16_f32 v88, v10, v3
	global_load_dword v3, v[8:9], off offset:64
	global_load_dword v10, v[8:9], off offset:192
	s_waitcnt vmcnt(1)
	v_xor_b32_e32 v3, 0x80000000, v3
	s_waitcnt vmcnt(0)
	v_xor_b32_e32 v10, 0x80000000, v10
	v_cvt_pk_bf16_f32 v89, v3, v10
	global_load_dword v3, v[6:7], off offset:196
	global_load_dword v10, v[6:7], off offset:68
	s_waitcnt vmcnt(0)
	v_cvt_pk_bf16_f32 v90, v10, v3
	global_load_dword v3, v[8:9], off offset:68
	global_load_dword v10, v[8:9], off offset:196
	s_waitcnt vmcnt(1)
	v_xor_b32_e32 v3, 0x80000000, v3
	s_waitcnt vmcnt(0)
	v_xor_b32_e32 v10, 0x80000000, v10
	v_cvt_pk_bf16_f32 v91, v3, v10
	global_load_dword v3, v[6:7], off offset:224
	global_load_dword v10, v[6:7], off offset:96
	s_waitcnt vmcnt(0)
	v_cvt_pk_bf16_f32 v92, v10, v3
	global_load_dword v3, v[8:9], off offset:96
	global_load_dword v10, v[8:9], off offset:224
	s_waitcnt vmcnt(1)
	v_xor_b32_e32 v3, 0x80000000, v3
	s_waitcnt vmcnt(0)
	v_xor_b32_e32 v10, 0x80000000, v10
	v_cvt_pk_bf16_f32 v93, v3, v10
	global_load_dword v3, v[6:7], off offset:228
	s_nop 0
	global_load_dword v6, v[6:7], off offset:100
	s_waitcnt vmcnt(0)
	v_cvt_pk_bf16_f32 v94, v6, v3
	global_load_dword v3, v[8:9], off offset:100
	global_load_dword v6, v[8:9], off offset:228
	s_waitcnt vmcnt(1)
	v_xor_b32_e32 v3, 0x80000000, v3
	s_waitcnt vmcnt(0)
	v_xor_b32_e32 v6, 0x80000000, v6
	v_cvt_pk_bf16_f32 v95, v3, v6
	s_and_saveexec_b64 s[6:7], vcc
	s_cbranch_execz .LBB0_96
	s_load_dwordx2 s[8:9], s[92:93], 0x70
	v_lshlrev_b32_e32 v3, 2, v1
	v_lshl_or_b32 v2, v2, 4, v3
	s_movk_i32 s0, 0x2200
	v_mov_b32_e32 v3, v159
	s_waitcnt lgkmcnt(0)
	global_load_dwordx4 v[96:99], v2, s[8:9]
	v_mul_lo_u32 v2, v27, s0
	v_add_u32_e32 v10, 0, v2
	v_lshlrev_b32_e32 v2, 3, v26
	v_mul_f32_e32 v115, v4, v5
	v_lshl_add_u64 v[2:3], s[90:91], 0, v[2:3]
	v_lshlrev_b32_e32 v4, 3, v25
	v_mov_b32_e32 v5, v159
	v_lshl_add_u64 v[2:3], v[2:3], 0, v[4:5]
	s_mov_b64 s[8:9], 0xbb00000
	v_lshl_add_u64 v[116:117], v[2:3], 0, s[8:9]
	v_lshrrev_b32_e32 v2, 1, v24
	v_and_b32_e32 v5, 12, v2
	v_lshlrev_b32_e32 v2, 1, v1
	v_mov_b32_e32 v3, v159
	v_lshl_add_u64 v[2:3], s[90:91], 0, v[2:3]
	s_mov_b64 s[0:1], 0x7300000
	v_lshl_add_u64 v[6:7], v[2:3], 0, s[0:1]
	v_lshlrev_b32_e32 v8, 1, v33
	v_mov_b32_e32 v9, v159
	v_lshl_add_u64 v[118:119], v[6:7], 0, v[8:9]
	v_lshl_add_u64 v[120:121], v[6:7], 0, v[158:159]
	v_lshl_add_u64 v[2:3], v[2:3], 0, v[158:159]
	s_mov_b64 s[8:9], 0x9300000
	v_lshlrev_b32_e32 v6, 7, v165
	v_add_u32_e32 v1, v10, v4
	v_and_b32_e32 v4, 48, v24
	v_lshl_add_u64 v[122:123], v[2:3], 0, s[8:9]
	v_mul_u32_u24_e32 v3, 0x110, v0
	v_or_b32_e32 v158, v6, v0
	v_lshlrev_b32_e32 v0, 4, v24
	v_mul_f32_e32 v113, v30, v31
	v_and_b32_e32 v11, 3, v24
	v_add_u32_e32 v4, v10, v4
	v_mul_u32_u24_e32 v2, 0x1100, v32
	v_and_or_b32 v0, v0, 64, v6
	v_mov_b32_e32 v124, v113
	v_mov_b32_e32 v125, v112
	v_mov_b32_e32 v126, v115
	v_mov_b32_e32 v127, v114
	v_or3_b32 v174, v0, v5, v11
	v_lshl_or_b32 v128, v165, 1, v32
	s_mov_b32 s10, 0
	s_mov_b64 s[8:9], 0
	v_add_u32_e32 v175, v1, v2
	v_add_u32_e32 v176, v4, v3
	v_add_u32_e32 v190, s10, v174
	v_add_u32_e32 v191, s10, v158
	v_ashrrev_i32_e32 v189, 31, v128
	v_mov_b32_e32 v188, v128
	v_lshlrev_b64 v[188:189], 15, v[188:189]
	v_lshl_add_u64 v[188:189], v[116:117], 0, v[188:189]
	global_load_dwordx2 v[152:153], v[188:189], off
	global_load_dwordx2 v[154:155], v[188:189], off offset:256
	v_mov_b32_e32 v188, v190
	v_ashrrev_i32_e32 v189, 31, v188
	v_lshlrev_b64 v[188:189], 11, v[188:189]
	v_lshl_add_u64 v[188:189], v[118:119], 0, v[188:189]
	global_load_dwordx4 v[100:103], v[188:189], off
	v_add_u32_e32 v188, 16, v190
	v_ashrrev_i32_e32 v189, 31, v188
	v_lshlrev_b64 v[188:189], 11, v[188:189]
	v_lshl_add_u64 v[188:189], v[118:119], 0, v[188:189]
	global_load_dwordx4 v[104:107], v[188:189], off
	v_add_u32_e32 v188, 32, v190
	v_ashrrev_i32_e32 v189, 31, v188
	v_lshlrev_b64 v[188:189], 11, v[188:189]
	v_lshl_add_u64 v[188:189], v[118:119], 0, v[188:189]
	global_load_dwordx4 v[108:111], v[188:189], off
	v_add_u32_e32 v188, 48, v190
	v_ashrrev_i32_e32 v189, 31, v188
	v_lshlrev_b64 v[188:189], 11, v[188:189]
	v_lshl_add_u64 v[188:189], v[118:119], 0, v[188:189]
	global_load_dwordx4 v[132:135], v[188:189], off
	v_mov_b32_e32 v188, v191
	v_ashrrev_i32_e32 v189, 31, v188
	v_lshlrev_b64 v[188:189], 11, v[188:189]
	v_lshl_add_u64 v[188:189], v[120:121], 0, v[188:189]
	global_load_dwordx2 v[136:137], v[188:189], off
	v_add_u32_e32 v188, 64, v191
	v_ashrrev_i32_e32 v189, 31, v188
	v_lshlrev_b64 v[188:189], 11, v[188:189]
	v_lshl_add_u64 v[188:189], v[120:121], 0, v[188:189]
	global_load_dwordx2 v[138:139], v[188:189], off
	v_add_u32_e32 v188, 16, v191
	v_ashrrev_i32_e32 v189, 31, v188
	v_lshlrev_b64 v[188:189], 11, v[188:189]
	v_lshl_add_u64 v[188:189], v[120:121], 0, v[188:189]
	global_load_dwordx2 v[140:141], v[188:189], off
	v_add_u32_e32 v188, 80, v191
	v_ashrrev_i32_e32 v189, 31, v188
	v_lshlrev_b64 v[188:189], 11, v[188:189]
	v_lshl_add_u64 v[188:189], v[120:121], 0, v[188:189]
	global_load_dwordx2 v[142:143], v[188:189], off
	v_add_u32_e32 v188, 32, v191
	v_ashrrev_i32_e32 v189, 31, v188
	v_lshlrev_b64 v[188:189], 11, v[188:189]
	v_lshl_add_u64 v[188:189], v[120:121], 0, v[188:189]
	global_load_dwordx2 v[144:145], v[188:189], off
	v_add_u32_e32 v188, 96, v191
	v_ashrrev_i32_e32 v189, 31, v188
	v_lshlrev_b64 v[188:189], 11, v[188:189]
	v_lshl_add_u64 v[188:189], v[120:121], 0, v[188:189]
	global_load_dwordx2 v[146:147], v[188:189], off
	v_add_u32_e32 v188, 48, v191
	v_ashrrev_i32_e32 v189, 31, v188
	v_lshlrev_b64 v[188:189], 11, v[188:189]
	v_lshl_add_u64 v[188:189], v[120:121], 0, v[188:189]
	global_load_dwordx2 v[148:149], v[188:189], off
	v_add_u32_e32 v188, 112, v191
	v_ashrrev_i32_e32 v189, 31, v188
	v_lshlrev_b64 v[188:189], 11, v[188:189]
	v_lshl_add_u64 v[188:189], v[120:121], 0, v[188:189]
	global_load_dwordx2 v[150:151], v[188:189], off
	s_waitcnt vmcnt(0)
.LBB0_95:
	v_add_u32_e32 v165, s54, v165
	v_cmp_lt_i32_e32 vcc, s36, v165
	v_add_u32_e32 v130, s84, v190
	v_add_u32_e32 v131, s84, v191
	v_add_u32_e32 v177, s5, v128
	s_or_b64 s[8:9], vcc, s[8:9]
	s_mov_b32 s101, 0x3d372713
	v_cndmask_b32_e32 v130, v130, v190, vcc
	v_cndmask_b32_e32 v131, v131, v191, vcc
	v_cndmask_b32_e32 v177, v177, v128, vcc
	s_waitcnt vmcnt(20)
	v_mov_b32_e32 v166, v152
	v_mov_b32_e32 v167, v153
	v_mov_b32_e32 v168, v154
	v_mov_b32_e32 v169, v155
	v_ashrrev_i32_e32 v189, 31, v177
	v_mov_b32_e32 v188, v177
	v_lshlrev_b64 v[188:189], 15, v[188:189]
	v_lshl_add_u64 v[188:189], v[116:117], 0, v[188:189]
	global_load_dwordx2 v[152:153], v[188:189], off
	global_load_dwordx2 v[154:155], v[188:189], off offset:256
	s_waitcnt vmcnt(21)
	v_mfma_f32_32x32x16_bf16 v[0:15], v[100:103], v[64:67], 0
	v_mfma_f32_32x32x16_bf16 v[16:31], v[100:103], v[68:71], 0
	v_mfma_f32_32x32x16_bf16 v[32:47], v[100:103], v[72:75], 0
	v_mfma_f32_32x32x16_bf16 v[48:63], v[100:103], v[76:79], 0
	v_mov_b32_e32 v188, v130
	v_ashrrev_i32_e32 v189, 31, v188
	v_lshlrev_b64 v[188:189], 11, v[188:189]
	v_lshl_add_u64 v[188:189], v[118:119], 0, v[188:189]
	global_load_dwordx4 v[100:103], v[188:189], off
	s_nop 5
	v_fma_f32 v170, v113, v166, v0
	v_fma_f32 v171, v113, v167, v16
	v_fma_f32 v172, v115, v168, v32
	v_fma_f32 v173, v115, v169, v48
	v_fma_f32 v170, -v112, v167, v170
	v_fma_f32 v171, v112, v166, v171
	v_fma_f32 v172, -v114, v169, v172
	v_fma_f32 v173, v114, v168, v173
	v_cvt_pk_bf16_f32 v178, v170, v172
	v_cvt_pk_bf16_f32 v179, v171, v173
	ds_write_b64 v175, v[178:179]
	v_fma_f32 v166, v113, v170, v1
	v_fma_f32 v167, v113, v171, v17
	v_fma_f32 v168, v115, v172, v33
	v_fma_f32 v169, v115, v173, v49
	v_fma_f32 v166, -v112, v171, v166
	v_fma_f32 v167, v112, v170, v167
	v_fma_f32 v168, -v114, v173, v168
	v_fma_f32 v169, v114, v172, v169
	v_cvt_pk_bf16_f32 v178, v166, v168
	v_cvt_pk_bf16_f32 v179, v167, v169
	ds_write_b64 v175, v[178:179] offset:272
	v_fma_f32 v170, v113, v166, v2
	v_fma_f32 v171, v113, v167, v18
	v_fma_f32 v172, v115, v168, v34
	v_fma_f32 v173, v115, v169, v50
	v_fma_f32 v170, -v112, v167, v170
	v_fma_f32 v171, v112, v166, v171
	v_fma_f32 v172, -v114, v169, v172
	v_fma_f32 v173, v114, v168, v173
	v_cvt_pk_bf16_f32 v178, v170, v172
	v_cvt_pk_bf16_f32 v179, v171, v173
	ds_write_b64 v175, v[178:179] offset:544
	v_fma_f32 v166, v113, v170, v3
	v_fma_f32 v167, v113, v171, v19
	v_fma_f32 v168, v115, v172, v35
	v_fma_f32 v169, v115, v173, v51
	v_fma_f32 v166, -v112, v171, v166
	v_fma_f32 v167, v112, v170, v167
	v_fma_f32 v168, -v114, v173, v168
	v_fma_f32 v169, v114, v172, v169
	v_cvt_pk_bf16_f32 v178, v166, v168
	v_cvt_pk_bf16_f32 v179, v167, v169
	ds_write_b64 v175, v[178:179] offset:816
	v_fma_f32 v170, v113, v166, v4
	v_fma_f32 v171, v113, v167, v20
	v_fma_f32 v172, v115, v168, v36
	v_fma_f32 v173, v115, v169, v52
	v_fma_f32 v170, -v112, v167, v170
	v_fma_f32 v171, v112, v166, v171
	v_fma_f32 v172, -v114, v169, v172
	v_fma_f32 v173, v114, v168, v173
	v_cvt_pk_bf16_f32 v178, v170, v172
	v_cvt_pk_bf16_f32 v179, v171, v173
	ds_write_b64 v175, v[178:179] offset:1088
	v_fma_f32 v166, v113, v170, v5
	v_fma_f32 v167, v113, v171, v21
	v_fma_f32 v168, v115, v172, v37
	v_fma_f32 v169, v115, v173, v53
	v_fma_f32 v166, -v112, v171, v166
	v_fma_f32 v167, v112, v170, v167
	v_fma_f32 v168, -v114, v173, v168
	v_fma_f32 v169, v114, v172, v169
	v_cvt_pk_bf16_f32 v178, v166, v168
	v_cvt_pk_bf16_f32 v179, v167, v169
	ds_write_b64 v175, v[178:179] offset:1360
	v_fma_f32 v170, v113, v166, v6
	v_fma_f32 v171, v113, v167, v22
	v_fma_f32 v172, v115, v168, v38
	v_fma_f32 v173, v115, v169, v54
	v_fma_f32 v170, -v112, v167, v170
	v_fma_f32 v171, v112, v166, v171
	v_fma_f32 v172, -v114, v169, v172
	v_fma_f32 v173, v114, v168, v173
	v_cvt_pk_bf16_f32 v178, v170, v172
	v_cvt_pk_bf16_f32 v179, v171, v173
	ds_write_b64 v175, v[178:179] offset:1632
	v_fma_f32 v166, v113, v170, v7
	v_fma_f32 v167, v113, v171, v23
	v_fma_f32 v168, v115, v172, v39
	v_fma_f32 v169, v115, v173, v55
	v_fma_f32 v166, -v112, v171, v166
	v_fma_f32 v167, v112, v170, v167
	v_fma_f32 v168, -v114, v173, v168
	v_fma_f32 v169, v114, v172, v169
	v_cvt_pk_bf16_f32 v178, v166, v168
	v_cvt_pk_bf16_f32 v179, v167, v169
	ds_write_b64 v175, v[178:179] offset:1904
	v_fma_f32 v170, v113, v166, v8
	v_fma_f32 v171, v113, v167, v24
	v_fma_f32 v172, v115, v168, v40
	v_fma_f32 v173, v115, v169, v56
	v_fma_f32 v170, -v112, v167, v170
	v_fma_f32 v171, v112, v166, v171
	v_fma_f32 v172, -v114, v169, v172
	v_fma_f32 v173, v114, v168, v173
	v_cvt_pk_bf16_f32 v178, v170, v172
	v_cvt_pk_bf16_f32 v179, v171, v173
	ds_write_b64 v175, v[178:179] offset:2176
	v_fma_f32 v166, v113, v170, v9
	v_fma_f32 v167, v113, v171, v25
	v_fma_f32 v168, v115, v172, v41
	v_fma_f32 v169, v115, v173, v57
	v_fma_f32 v166, -v112, v171, v166
	v_fma_f32 v167, v112, v170, v167
	v_fma_f32 v168, -v114, v173, v168
	v_fma_f32 v169, v114, v172, v169
	v_cvt_pk_bf16_f32 v178, v166, v168
	v_cvt_pk_bf16_f32 v179, v167, v169
	ds_write_b64 v175, v[178:179] offset:2448
	v_fma_f32 v170, v113, v166, v10
	v_fma_f32 v171, v113, v167, v26
	v_fma_f32 v172, v115, v168, v42
	v_fma_f32 v173, v115, v169, v58
	v_fma_f32 v170, -v112, v167, v170
	v_fma_f32 v171, v112, v166, v171
	v_fma_f32 v172, -v114, v169, v172
	v_fma_f32 v173, v114, v168, v173
	v_cvt_pk_bf16_f32 v178, v170, v172
	v_cvt_pk_bf16_f32 v179, v171, v173
	ds_write_b64 v175, v[178:179] offset:2720
	v_fma_f32 v166, v113, v170, v11
	v_fma_f32 v167, v113, v171, v27
	v_fma_f32 v168, v115, v172, v43
	v_fma_f32 v169, v115, v173, v59
	v_fma_f32 v166, -v112, v171, v166
	v_fma_f32 v167, v112, v170, v167
	v_fma_f32 v168, -v114, v173, v168
	v_fma_f32 v169, v114, v172, v169
	v_cvt_pk_bf16_f32 v178, v166, v168
	v_cvt_pk_bf16_f32 v179, v167, v169
	ds_write_b64 v175, v[178:179] offset:2992
	v_fma_f32 v170, v113, v166, v12
	v_fma_f32 v171, v113, v167, v28
	v_fma_f32 v172, v115, v168, v44
	v_fma_f32 v173, v115, v169, v60
	v_fma_f32 v170, -v112, v167, v170
	v_fma_f32 v171, v112, v166, v171
	v_fma_f32 v172, -v114, v169, v172
	v_fma_f32 v173, v114, v168, v173
	v_cvt_pk_bf16_f32 v178, v170, v172
	v_cvt_pk_bf16_f32 v179, v171, v173
	ds_write_b64 v175, v[178:179] offset:3264
	v_fma_f32 v166, v113, v170, v13
	v_fma_f32 v167, v113, v171, v29
	v_fma_f32 v168, v115, v172, v45
	v_fma_f32 v169, v115, v173, v61
	v_fma_f32 v166, -v112, v171, v166
	v_fma_f32 v167, v112, v170, v167
	v_fma_f32 v168, -v114, v173, v168
	v_fma_f32 v169, v114, v172, v169
	v_cvt_pk_bf16_f32 v178, v166, v168
	v_cvt_pk_bf16_f32 v179, v167, v169
	ds_write_b64 v175, v[178:179] offset:3536
	v_fma_f32 v170, v113, v166, v14
	v_fma_f32 v171, v113, v167, v30
	v_fma_f32 v172, v115, v168, v46
	v_fma_f32 v173, v115, v169, v62
	v_fma_f32 v170, -v112, v167, v170
	v_fma_f32 v171, v112, v166, v171
	v_fma_f32 v172, -v114, v169, v172
	v_fma_f32 v173, v114, v168, v173
	v_cvt_pk_bf16_f32 v178, v170, v172
	v_cvt_pk_bf16_f32 v179, v171, v173
	ds_write_b64 v175, v[178:179] offset:3808
	v_fma_f32 v166, v113, v170, v15
	v_fma_f32 v167, v113, v171, v31
	v_fma_f32 v168, v115, v172, v47
	v_fma_f32 v169, v115, v173, v63
	v_fma_f32 v166, -v112, v171, v166
	v_fma_f32 v167, v112, v170, v167
	v_fma_f32 v168, -v114, v173, v168
	v_fma_f32 v169, v114, v172, v169
	v_cvt_pk_bf16_f32 v178, v166, v168
	v_cvt_pk_bf16_f32 v179, v167, v169
	ds_write_b64 v175, v[178:179] offset:4080
	s_waitcnt vmcnt(21)
	v_mfma_f32_32x32x16_bf16 v[0:15], v[104:107], v[64:67], 0
	v_mfma_f32_32x32x16_bf16 v[16:31], v[104:107], v[68:71], 0
	v_mfma_f32_32x32x16_bf16 v[32:47], v[104:107], v[72:75], 0
	v_mfma_f32_32x32x16_bf16 v[48:63], v[104:107], v[76:79], 0
	v_add_u32_e32 v188, 16, v130
	v_ashrrev_i32_e32 v189, 31, v188
	v_lshlrev_b64 v[188:189], 11, v[188:189]
	v_lshl_add_u64 v[188:189], v[118:119], 0, v[188:189]
	global_load_dwordx4 v[104:107], v[188:189], off
	ds_read_b128 v[214:217], v176
	ds_read_b128 v[218:221], v176 offset:64
	ds_read_b128 v[222:225], v176 offset:128
	ds_read_b128 v[226:229], v176 offset:192
	ds_read_b128 v[230:233], v176 offset:4352
	ds_read_b128 v[234:237], v176 offset:4416
	ds_read_b128 v[238:241], v176 offset:4480
	ds_read_b128 v[242:245], v176 offset:4544
	s_waitcnt lgkmcnt(7)
	v_mfma_f32_16x16x32_bf16 v[180:183], v[80:83], v[214:217], 0
	s_waitcnt lgkmcnt(6)
	v_mfma_f32_16x16x32_bf16 v[180:183], v[84:87], v[218:221], v[180:183]
	s_waitcnt lgkmcnt(5)
	v_mfma_f32_16x16x32_bf16 v[180:183], v[88:91], v[222:225], v[180:183]
	s_waitcnt lgkmcnt(4)
	v_mfma_f32_16x16x32_bf16 v[180:183], v[92:95], v[226:229], v[180:183]
	s_waitcnt lgkmcnt(3)
	v_mfma_f32_16x16x32_bf16 v[184:187], v[80:83], v[230:233], 0
	s_waitcnt lgkmcnt(2)
	v_mfma_f32_16x16x32_bf16 v[184:187], v[84:87], v[234:237], v[184:187]
	s_waitcnt lgkmcnt(1)
	v_mfma_f32_16x16x32_bf16 v[184:187], v[88:91], v[238:241], v[184:187]
	s_waitcnt lgkmcnt(0)
	v_mfma_f32_16x16x32_bf16 v[184:187], v[92:95], v[242:245], v[184:187]
	s_waitcnt vmcnt(18)
	v_lshlrev_b32_e32 v246, 16, v136
	v_and_b32_e32 v247, 0xffff0000, v136
	v_lshlrev_b32_e32 v248, 16, v137
	v_and_b32_e32 v249, 0xffff0000, v137
	v_lshlrev_b32_e32 v250, 16, v138
	v_and_b32_e32 v251, 0xffff0000, v138
	v_lshlrev_b32_e32 v252, 16, v139
	v_and_b32_e32 v253, 0xffff0000, v139
	v_mov_b32_e32 v202, v191
	v_ashrrev_i32_e32 v203, 31, v202
	v_lshlrev_b64 v[202:203], 11, v[202:203]
	v_lshl_add_u64 v[202:203], v[122:123], 0, v[202:203]
	v_add_u32_e32 v204, 64, v191
	v_ashrrev_i32_e32 v205, 31, v204
	v_lshlrev_b64 v[204:205], 11, v[204:205]
	v_lshl_add_u64 v[204:205], v[122:123], 0, v[204:205]
	v_fma_f32 v180, v96, v246, v180
	v_fma_f32 v181, v97, v247, v181
	v_fma_f32 v182, v98, v248, v182
	v_fma_f32 v183, v99, v249, v183
	v_fma_f32 v184, v96, v250, v184
	v_fma_f32 v185, v97, v251, v185
	v_fma_f32 v186, v98, v252, v186
	v_fma_f32 v187, v99, v253, v187
	v_mul_f32_e32 v214, v180, v180
	v_mul_f32_e32 v215, v181, v181
	v_mul_f32_e32 v216, v182, v182
	v_mul_f32_e32 v217, v183, v183
	v_mul_f32_e32 v218, v184, v184
	v_mul_f32_e32 v219, v185, v185
	v_mul_f32_e32 v220, v186, v186
	v_mul_f32_e32 v221, v187, v187
	v_fma_f32 v214, v214, s101, 1.0
	v_fma_f32 v215, v215, s101, 1.0
	v_fma_f32 v216, v216, s101, 1.0
	v_fma_f32 v217, v217, s101, 1.0
	v_fma_f32 v218, v218, s101, 1.0
	v_fma_f32 v219, v219, s101, 1.0
	v_fma_f32 v220, v220, s101, 1.0
	v_fma_f32 v221, v221, s101, 1.0
	v_mul_f32_e32 v214, v214, v180
	v_mul_f32_e32 v215, v215, v181
	v_mul_f32_e32 v216, v216, v182
	v_mul_f32_e32 v217, v217, v183
	v_mul_f32_e32 v218, v218, v184
	v_mul_f32_e32 v219, v219, v185
	v_mul_f32_e32 v220, v220, v186
	v_mul_f32_e32 v221, v221, v187
	v_mul_f32_e32 v214, 0x40135761, v214
	v_mul_f32_e32 v215, 0x40135761, v215
	v_mul_f32_e32 v216, 0x40135761, v216
	v_mul_f32_e32 v217, 0x40135761, v217
	v_mul_f32_e32 v218, 0x40135761, v218
	v_mul_f32_e32 v219, 0x40135761, v219
	v_mul_f32_e32 v220, 0x40135761, v220
	v_mul_f32_e32 v221, 0x40135761, v221
	v_exp_f32_e32 v214, v214
	v_exp_f32_e32 v215, v215
	v_exp_f32_e32 v216, v216
	v_exp_f32_e32 v217, v217
	v_exp_f32_e32 v218, v218
	v_exp_f32_e32 v219, v219
	v_exp_f32_e32 v220, v220
	v_exp_f32_e32 v221, v221
	v_mul_f32_e32 v222, 0.5, v180
	v_mul_f32_e32 v223, 0.5, v181
	v_mul_f32_e32 v224, 0.5, v182
	v_mul_f32_e32 v225, 0.5, v183
	v_mul_f32_e32 v226, 0.5, v184
	v_mul_f32_e32 v227, 0.5, v185
	v_mul_f32_e32 v228, 0.5, v186
	v_mul_f32_e32 v229, 0.5, v187
	v_add_f32_e32 v214, 1.0, v214
	v_add_f32_e32 v215, 1.0, v215
	v_add_f32_e32 v216, 1.0, v216
	v_add_f32_e32 v217, 1.0, v217
	v_add_f32_e32 v218, 1.0, v218
	v_add_f32_e32 v219, 1.0, v219
	v_add_f32_e32 v220, 1.0, v220
	v_add_f32_e32 v221, 1.0, v221
	v_rcp_f32_e32 v214, v214
	v_rcp_f32_e32 v215, v215
	v_rcp_f32_e32 v216, v216
	v_rcp_f32_e32 v217, v217
	v_rcp_f32_e32 v218, v218
	v_rcp_f32_e32 v219, v219
	v_rcp_f32_e32 v220, v220
	v_rcp_f32_e32 v221, v221
	s_nop 0
	v_fma_f32 v214, v214, -2.0, 1.0
	v_fma_f32 v215, v215, -2.0, 1.0
	v_fma_f32 v216, v216, -2.0, 1.0
	v_fma_f32 v217, v217, -2.0, 1.0
	v_fma_f32 v218, v218, -2.0, 1.0
	v_fma_f32 v219, v219, -2.0, 1.0
	v_fma_f32 v220, v220, -2.0, 1.0
	v_fma_f32 v221, v221, -2.0, 1.0
	v_fma_f32 v180, v222, v214, v222
	v_fma_f32 v181, v223, v215, v223
	v_fma_f32 v182, v224, v216, v224
	v_fma_f32 v183, v225, v217, v225
	v_fma_f32 v184, v226, v218, v226
	v_fma_f32 v185, v227, v219, v227
	v_fma_f32 v186, v228, v220, v228
	v_fma_f32 v187, v229, v221, v229
	v_cvt_pk_bf16_f32 v214, v180, v181
	v_cvt_pk_bf16_f32 v215, v182, v183
	v_cvt_pk_bf16_f32 v216, v184, v185
	v_cvt_pk_bf16_f32 v217, v186, v187
	global_store_dwordx2 v[202:203], v[214:215], off
	global_store_dwordx2 v[204:205], v[216:217], off
	v_mov_b32_e32 v188, v131
	v_ashrrev_i32_e32 v189, 31, v188
	v_lshlrev_b64 v[188:189], 11, v[188:189]
	v_lshl_add_u64 v[188:189], v[120:121], 0, v[188:189]
	global_load_dwordx2 v[136:137], v[188:189], off
	v_add_u32_e32 v188, 64, v131
	v_ashrrev_i32_e32 v189, 31, v188
	v_lshlrev_b64 v[188:189], 11, v[188:189]
	v_lshl_add_u64 v[188:189], v[120:121], 0, v[188:189]
	global_load_dwordx2 v[138:139], v[188:189], off
	v_fma_f32 v170, v113, v166, v0
	v_fma_f32 v171, v113, v167, v16
	v_fma_f32 v172, v115, v168, v32
	v_fma_f32 v173, v115, v169, v48
	v_fma_f32 v170, -v112, v167, v170
	v_fma_f32 v171, v112, v166, v171
	v_fma_f32 v172, -v114, v169, v172
	v_fma_f32 v173, v114, v168, v173
	v_cvt_pk_bf16_f32 v178, v170, v172
	v_cvt_pk_bf16_f32 v179, v171, v173
	ds_write_b64 v175, v[178:179]
	v_fma_f32 v166, v113, v170, v1
	v_fma_f32 v167, v113, v171, v17
	v_fma_f32 v168, v115, v172, v33
	v_fma_f32 v169, v115, v173, v49
	v_fma_f32 v166, -v112, v171, v166
	v_fma_f32 v167, v112, v170, v167
	v_fma_f32 v168, -v114, v173, v168
	v_fma_f32 v169, v114, v172, v169
	v_cvt_pk_bf16_f32 v178, v166, v168
	v_cvt_pk_bf16_f32 v179, v167, v169
	ds_write_b64 v175, v[178:179] offset:272
	v_fma_f32 v170, v113, v166, v2
	v_fma_f32 v171, v113, v167, v18
	v_fma_f32 v172, v115, v168, v34
	v_fma_f32 v173, v115, v169, v50
	v_fma_f32 v170, -v112, v167, v170
	v_fma_f32 v171, v112, v166, v171
	v_fma_f32 v172, -v114, v169, v172
	v_fma_f32 v173, v114, v168, v173
	v_cvt_pk_bf16_f32 v178, v170, v172
	v_cvt_pk_bf16_f32 v179, v171, v173
	ds_write_b64 v175, v[178:179] offset:544
	v_fma_f32 v166, v113, v170, v3
	v_fma_f32 v167, v113, v171, v19
	v_fma_f32 v168, v115, v172, v35
	v_fma_f32 v169, v115, v173, v51
	v_fma_f32 v166, -v112, v171, v166
	v_fma_f32 v167, v112, v170, v167
	v_fma_f32 v168, -v114, v173, v168
	v_fma_f32 v169, v114, v172, v169
	v_cvt_pk_bf16_f32 v178, v166, v168
	v_cvt_pk_bf16_f32 v179, v167, v169
	ds_write_b64 v175, v[178:179] offset:816
	v_fma_f32 v170, v113, v166, v4
	v_fma_f32 v171, v113, v167, v20
	v_fma_f32 v172, v115, v168, v36
	v_fma_f32 v173, v115, v169, v52
	v_fma_f32 v170, -v112, v167, v170
	v_fma_f32 v171, v112, v166, v171
	v_fma_f32 v172, -v114, v169, v172
	v_fma_f32 v173, v114, v168, v173
	v_cvt_pk_bf16_f32 v178, v170, v172
	v_cvt_pk_bf16_f32 v179, v171, v173
	ds_write_b64 v175, v[178:179] offset:1088
	v_fma_f32 v166, v113, v170, v5
	v_fma_f32 v167, v113, v171, v21
	v_fma_f32 v168, v115, v172, v37
	v_fma_f32 v169, v115, v173, v53
	v_fma_f32 v166, -v112, v171, v166
	v_fma_f32 v167, v112, v170, v167
	v_fma_f32 v168, -v114, v173, v168
	v_fma_f32 v169, v114, v172, v169
	v_cvt_pk_bf16_f32 v178, v166, v168
	v_cvt_pk_bf16_f32 v179, v167, v169
	ds_write_b64 v175, v[178:179] offset:1360
	v_fma_f32 v170, v113, v166, v6
	v_fma_f32 v171, v113, v167, v22
	v_fma_f32 v172, v115, v168, v38
	v_fma_f32 v173, v115, v169, v54
	v_fma_f32 v170, -v112, v167, v170
	v_fma_f32 v171, v112, v166, v171
	v_fma_f32 v172, -v114, v169, v172
	v_fma_f32 v173, v114, v168, v173
	v_cvt_pk_bf16_f32 v178, v170, v172
	v_cvt_pk_bf16_f32 v179, v171, v173
	ds_write_b64 v175, v[178:179] offset:1632
	v_fma_f32 v166, v113, v170, v7
	v_fma_f32 v167, v113, v171, v23
	v_fma_f32 v168, v115, v172, v39
	v_fma_f32 v169, v115, v173, v55
	v_fma_f32 v166, -v112, v171, v166
	v_fma_f32 v167, v112, v170, v167
	v_fma_f32 v168, -v114, v173, v168
	v_fma_f32 v169, v114, v172, v169
	v_cvt_pk_bf16_f32 v178, v166, v168
	v_cvt_pk_bf16_f32 v179, v167, v169
	ds_write_b64 v175, v[178:179] offset:1904
	v_fma_f32 v170, v113, v166, v8
	v_fma_f32 v171, v113, v167, v24
	v_fma_f32 v172, v115, v168, v40
	v_fma_f32 v173, v115, v169, v56
	v_fma_f32 v170, -v112, v167, v170
	v_fma_f32 v171, v112, v166, v171
	v_fma_f32 v172, -v114, v169, v172
	v_fma_f32 v173, v114, v168, v173
	v_cvt_pk_bf16_f32 v178, v170, v172
	v_cvt_pk_bf16_f32 v179, v171, v173
	ds_write_b64 v175, v[178:179] offset:2176
	v_fma_f32 v166, v113, v170, v9
	v_fma_f32 v167, v113, v171, v25
	v_fma_f32 v168, v115, v172, v41
	v_fma_f32 v169, v115, v173, v57
	v_fma_f32 v166, -v112, v171, v166
	v_fma_f32 v167, v112, v170, v167
	v_fma_f32 v168, -v114, v173, v168
	v_fma_f32 v169, v114, v172, v169
	v_cvt_pk_bf16_f32 v178, v166, v168
	v_cvt_pk_bf16_f32 v179, v167, v169
	ds_write_b64 v175, v[178:179] offset:2448
	v_fma_f32 v170, v113, v166, v10
	v_fma_f32 v171, v113, v167, v26
	v_fma_f32 v172, v115, v168, v42
	v_fma_f32 v173, v115, v169, v58
	v_fma_f32 v170, -v112, v167, v170
	v_fma_f32 v171, v112, v166, v171
	v_fma_f32 v172, -v114, v169, v172
	v_fma_f32 v173, v114, v168, v173
	v_cvt_pk_bf16_f32 v178, v170, v172
	v_cvt_pk_bf16_f32 v179, v171, v173
	ds_write_b64 v175, v[178:179] offset:2720
	v_fma_f32 v166, v113, v170, v11
	v_fma_f32 v167, v113, v171, v27
	v_fma_f32 v168, v115, v172, v43
	v_fma_f32 v169, v115, v173, v59
	v_fma_f32 v166, -v112, v171, v166
	v_fma_f32 v167, v112, v170, v167
	v_fma_f32 v168, -v114, v173, v168
	v_fma_f32 v169, v114, v172, v169
	v_cvt_pk_bf16_f32 v178, v166, v168
	v_cvt_pk_bf16_f32 v179, v167, v169
	ds_write_b64 v175, v[178:179] offset:2992
	v_fma_f32 v170, v113, v166, v12
	v_fma_f32 v171, v113, v167, v28
	v_fma_f32 v172, v115, v168, v44
	v_fma_f32 v173, v115, v169, v60
	v_fma_f32 v170, -v112, v167, v170
	v_fma_f32 v171, v112, v166, v171
	v_fma_f32 v172, -v114, v169, v172
	v_fma_f32 v173, v114, v168, v173
	v_cvt_pk_bf16_f32 v178, v170, v172
	v_cvt_pk_bf16_f32 v179, v171, v173
	ds_write_b64 v175, v[178:179] offset:3264
	v_fma_f32 v166, v113, v170, v13
	v_fma_f32 v167, v113, v171, v29
	v_fma_f32 v168, v115, v172, v45
	v_fma_f32 v169, v115, v173, v61
	v_fma_f32 v166, -v112, v171, v166
	v_fma_f32 v167, v112, v170, v167
	v_fma_f32 v168, -v114, v173, v168
	v_fma_f32 v169, v114, v172, v169
	v_cvt_pk_bf16_f32 v178, v166, v168
	v_cvt_pk_bf16_f32 v179, v167, v169
	ds_write_b64 v175, v[178:179] offset:3536
	v_fma_f32 v170, v113, v166, v14
	v_fma_f32 v171, v113, v167, v30
	v_fma_f32 v172, v115, v168, v46
	v_fma_f32 v173, v115, v169, v62
	v_fma_f32 v170, -v112, v167, v170
	v_fma_f32 v171, v112, v166, v171
	v_fma_f32 v172, -v114, v169, v172
	v_fma_f32 v173, v114, v168, v173
	v_cvt_pk_bf16_f32 v178, v170, v172
	v_cvt_pk_bf16_f32 v179, v171, v173
	ds_write_b64 v175, v[178:179] offset:3808
	v_fma_f32 v166, v113, v170, v15
	v_fma_f32 v167, v113, v171, v31
	v_fma_f32 v168, v115, v172, v47
	v_fma_f32 v169, v115, v173, v63
	v_fma_f32 v166, -v112, v171, v166
	v_fma_f32 v167, v112, v170, v167
	v_fma_f32 v168, -v114, v173, v168
	v_fma_f32 v169, v114, v172, v169
	v_cvt_pk_bf16_f32 v178, v166, v168
	v_cvt_pk_bf16_f32 v179, v167, v169
	ds_write_b64 v175, v[178:179] offset:4080
	s_waitcnt vmcnt(21)
	v_mfma_f32_32x32x16_bf16 v[0:15], v[108:111], v[64:67], 0
	v_mfma_f32_32x32x16_bf16 v[16:31], v[108:111], v[68:71], 0
	v_mfma_f32_32x32x16_bf16 v[32:47], v[108:111], v[72:75], 0
	v_mfma_f32_32x32x16_bf16 v[48:63], v[108:111], v[76:79], 0
	v_add_u32_e32 v188, 32, v130
	v_ashrrev_i32_e32 v189, 31, v188
	v_lshlrev_b64 v[188:189], 11, v[188:189]
	v_lshl_add_u64 v[188:189], v[118:119], 0, v[188:189]
	global_load_dwordx4 v[108:111], v[188:189], off
	ds_read_b128 v[214:217], v176
	ds_read_b128 v[218:221], v176 offset:64
	ds_read_b128 v[222:225], v176 offset:128
	ds_read_b128 v[226:229], v176 offset:192
	ds_read_b128 v[230:233], v176 offset:4352
	ds_read_b128 v[234:237], v176 offset:4416
	ds_read_b128 v[238:241], v176 offset:4480
	ds_read_b128 v[242:245], v176 offset:4544
	s_waitcnt lgkmcnt(7)
	v_mfma_f32_16x16x32_bf16 v[180:183], v[80:83], v[214:217], 0
	s_waitcnt lgkmcnt(6)
	v_mfma_f32_16x16x32_bf16 v[180:183], v[84:87], v[218:221], v[180:183]
	s_waitcnt lgkmcnt(5)
	v_mfma_f32_16x16x32_bf16 v[180:183], v[88:91], v[222:225], v[180:183]
	s_waitcnt lgkmcnt(4)
	v_mfma_f32_16x16x32_bf16 v[180:183], v[92:95], v[226:229], v[180:183]
	s_waitcnt lgkmcnt(3)
	v_mfma_f32_16x16x32_bf16 v[184:187], v[80:83], v[230:233], 0
	s_waitcnt lgkmcnt(2)
	v_mfma_f32_16x16x32_bf16 v[184:187], v[84:87], v[234:237], v[184:187]
	s_waitcnt lgkmcnt(1)
	v_mfma_f32_16x16x32_bf16 v[184:187], v[88:91], v[238:241], v[184:187]
	s_waitcnt lgkmcnt(0)
	v_mfma_f32_16x16x32_bf16 v[184:187], v[92:95], v[242:245], v[184:187]
	s_waitcnt vmcnt(18)
	v_lshlrev_b32_e32 v246, 16, v140
	v_and_b32_e32 v247, 0xffff0000, v140
	v_lshlrev_b32_e32 v248, 16, v141
	v_and_b32_e32 v249, 0xffff0000, v141
	v_lshlrev_b32_e32 v250, 16, v142
	v_and_b32_e32 v251, 0xffff0000, v142
	v_lshlrev_b32_e32 v252, 16, v143
	v_and_b32_e32 v253, 0xffff0000, v143
	v_add_u32_e32 v202, 16, v191
	v_ashrrev_i32_e32 v203, 31, v202
	v_lshlrev_b64 v[202:203], 11, v[202:203]
	v_lshl_add_u64 v[202:203], v[122:123], 0, v[202:203]
	v_add_u32_e32 v204, 80, v191
	v_ashrrev_i32_e32 v205, 31, v204
	v_lshlrev_b64 v[204:205], 11, v[204:205]
	v_lshl_add_u64 v[204:205], v[122:123], 0, v[204:205]
	v_fma_f32 v180, v96, v246, v180
	v_fma_f32 v181, v97, v247, v181
	v_fma_f32 v182, v98, v248, v182
	v_fma_f32 v183, v99, v249, v183
	v_fma_f32 v184, v96, v250, v184
	v_fma_f32 v185, v97, v251, v185
	v_fma_f32 v186, v98, v252, v186
	v_fma_f32 v187, v99, v253, v187
	v_mul_f32_e32 v214, v180, v180
	v_mul_f32_e32 v215, v181, v181
	v_mul_f32_e32 v216, v182, v182
	v_mul_f32_e32 v217, v183, v183
	v_mul_f32_e32 v218, v184, v184
	v_mul_f32_e32 v219, v185, v185
	v_mul_f32_e32 v220, v186, v186
	v_mul_f32_e32 v221, v187, v187
	v_fma_f32 v214, v214, s101, 1.0
	v_fma_f32 v215, v215, s101, 1.0
	v_fma_f32 v216, v216, s101, 1.0
	v_fma_f32 v217, v217, s101, 1.0
	v_fma_f32 v218, v218, s101, 1.0
	v_fma_f32 v219, v219, s101, 1.0
	v_fma_f32 v220, v220, s101, 1.0
	v_fma_f32 v221, v221, s101, 1.0
	v_mul_f32_e32 v214, v214, v180
	v_mul_f32_e32 v215, v215, v181
	v_mul_f32_e32 v216, v216, v182
	v_mul_f32_e32 v217, v217, v183
	v_mul_f32_e32 v218, v218, v184
	v_mul_f32_e32 v219, v219, v185
	v_mul_f32_e32 v220, v220, v186
	v_mul_f32_e32 v221, v221, v187
	v_mul_f32_e32 v214, 0x40135761, v214
	v_mul_f32_e32 v215, 0x40135761, v215
	v_mul_f32_e32 v216, 0x40135761, v216
	v_mul_f32_e32 v217, 0x40135761, v217
	v_mul_f32_e32 v218, 0x40135761, v218
	v_mul_f32_e32 v219, 0x40135761, v219
	v_mul_f32_e32 v220, 0x40135761, v220
	v_mul_f32_e32 v221, 0x40135761, v221
	v_exp_f32_e32 v214, v214
	v_exp_f32_e32 v215, v215
	v_exp_f32_e32 v216, v216
	v_exp_f32_e32 v217, v217
	v_exp_f32_e32 v218, v218
	v_exp_f32_e32 v219, v219
	v_exp_f32_e32 v220, v220
	v_exp_f32_e32 v221, v221
	v_mul_f32_e32 v222, 0.5, v180
	v_mul_f32_e32 v223, 0.5, v181
	v_mul_f32_e32 v224, 0.5, v182
	v_mul_f32_e32 v225, 0.5, v183
	v_mul_f32_e32 v226, 0.5, v184
	v_mul_f32_e32 v227, 0.5, v185
	v_mul_f32_e32 v228, 0.5, v186
	v_mul_f32_e32 v229, 0.5, v187
	v_add_f32_e32 v214, 1.0, v214
	v_add_f32_e32 v215, 1.0, v215
	v_add_f32_e32 v216, 1.0, v216
	v_add_f32_e32 v217, 1.0, v217
	v_add_f32_e32 v218, 1.0, v218
	v_add_f32_e32 v219, 1.0, v219
	v_add_f32_e32 v220, 1.0, v220
	v_add_f32_e32 v221, 1.0, v221
	v_rcp_f32_e32 v214, v214
	v_rcp_f32_e32 v215, v215
	v_rcp_f32_e32 v216, v216
	v_rcp_f32_e32 v217, v217
	v_rcp_f32_e32 v218, v218
	v_rcp_f32_e32 v219, v219
	v_rcp_f32_e32 v220, v220
	v_rcp_f32_e32 v221, v221
	s_nop 0
	v_fma_f32 v214, v214, -2.0, 1.0
	v_fma_f32 v215, v215, -2.0, 1.0
	v_fma_f32 v216, v216, -2.0, 1.0
	v_fma_f32 v217, v217, -2.0, 1.0
	v_fma_f32 v218, v218, -2.0, 1.0
	v_fma_f32 v219, v219, -2.0, 1.0
	v_fma_f32 v220, v220, -2.0, 1.0
	v_fma_f32 v221, v221, -2.0, 1.0
	v_fma_f32 v180, v222, v214, v222
	v_fma_f32 v181, v223, v215, v223
	v_fma_f32 v182, v224, v216, v224
	v_fma_f32 v183, v225, v217, v225
	v_fma_f32 v184, v226, v218, v226
	v_fma_f32 v185, v227, v219, v227
	v_fma_f32 v186, v228, v220, v228
	v_fma_f32 v187, v229, v221, v229
	v_cvt_pk_bf16_f32 v214, v180, v181
	v_cvt_pk_bf16_f32 v215, v182, v183
	v_cvt_pk_bf16_f32 v216, v184, v185
	v_cvt_pk_bf16_f32 v217, v186, v187
	global_store_dwordx2 v[202:203], v[214:215], off
	global_store_dwordx2 v[204:205], v[216:217], off
	v_add_u32_e32 v188, 16, v131
	v_ashrrev_i32_e32 v189, 31, v188
	v_lshlrev_b64 v[188:189], 11, v[188:189]
	v_lshl_add_u64 v[188:189], v[120:121], 0, v[188:189]
	global_load_dwordx2 v[140:141], v[188:189], off
	v_add_u32_e32 v188, 80, v131
	v_ashrrev_i32_e32 v189, 31, v188
	v_lshlrev_b64 v[188:189], 11, v[188:189]
	v_lshl_add_u64 v[188:189], v[120:121], 0, v[188:189]
	global_load_dwordx2 v[142:143], v[188:189], off
	v_fma_f32 v170, v113, v166, v0
	v_fma_f32 v171, v113, v167, v16
	v_fma_f32 v172, v115, v168, v32
	v_fma_f32 v173, v115, v169, v48
	v_fma_f32 v170, -v112, v167, v170
	v_fma_f32 v171, v112, v166, v171
	v_fma_f32 v172, -v114, v169, v172
	v_fma_f32 v173, v114, v168, v173
	v_cvt_pk_bf16_f32 v178, v170, v172
	v_cvt_pk_bf16_f32 v179, v171, v173
	ds_write_b64 v175, v[178:179]
	v_fma_f32 v166, v113, v170, v1
	v_fma_f32 v167, v113, v171, v17
	v_fma_f32 v168, v115, v172, v33
	v_fma_f32 v169, v115, v173, v49
	v_fma_f32 v166, -v112, v171, v166
	v_fma_f32 v167, v112, v170, v167
	v_fma_f32 v168, -v114, v173, v168
	v_fma_f32 v169, v114, v172, v169
	v_cvt_pk_bf16_f32 v178, v166, v168
	v_cvt_pk_bf16_f32 v179, v167, v169
	ds_write_b64 v175, v[178:179] offset:272
	v_fma_f32 v170, v113, v166, v2
	v_fma_f32 v171, v113, v167, v18
	v_fma_f32 v172, v115, v168, v34
	v_fma_f32 v173, v115, v169, v50
	v_fma_f32 v170, -v112, v167, v170
	v_fma_f32 v171, v112, v166, v171
	v_fma_f32 v172, -v114, v169, v172
	v_fma_f32 v173, v114, v168, v173
	v_cvt_pk_bf16_f32 v178, v170, v172
	v_cvt_pk_bf16_f32 v179, v171, v173
	ds_write_b64 v175, v[178:179] offset:544
	v_fma_f32 v166, v113, v170, v3
	v_fma_f32 v167, v113, v171, v19
	v_fma_f32 v168, v115, v172, v35
	v_fma_f32 v169, v115, v173, v51
	v_fma_f32 v166, -v112, v171, v166
	v_fma_f32 v167, v112, v170, v167
	v_fma_f32 v168, -v114, v173, v168
	v_fma_f32 v169, v114, v172, v169
	v_cvt_pk_bf16_f32 v178, v166, v168
	v_cvt_pk_bf16_f32 v179, v167, v169
	ds_write_b64 v175, v[178:179] offset:816
	v_fma_f32 v170, v113, v166, v4
	v_fma_f32 v171, v113, v167, v20
	v_fma_f32 v172, v115, v168, v36
	v_fma_f32 v173, v115, v169, v52
	v_fma_f32 v170, -v112, v167, v170
	v_fma_f32 v171, v112, v166, v171
	v_fma_f32 v172, -v114, v169, v172
	v_fma_f32 v173, v114, v168, v173
	v_cvt_pk_bf16_f32 v178, v170, v172
	v_cvt_pk_bf16_f32 v179, v171, v173
	ds_write_b64 v175, v[178:179] offset:1088
	v_fma_f32 v166, v113, v170, v5
	v_fma_f32 v167, v113, v171, v21
	v_fma_f32 v168, v115, v172, v37
	v_fma_f32 v169, v115, v173, v53
	v_fma_f32 v166, -v112, v171, v166
	v_fma_f32 v167, v112, v170, v167
	v_fma_f32 v168, -v114, v173, v168
	v_fma_f32 v169, v114, v172, v169
	v_cvt_pk_bf16_f32 v178, v166, v168
	v_cvt_pk_bf16_f32 v179, v167, v169
	ds_write_b64 v175, v[178:179] offset:1360
	v_fma_f32 v170, v113, v166, v6
	v_fma_f32 v171, v113, v167, v22
	v_fma_f32 v172, v115, v168, v38
	v_fma_f32 v173, v115, v169, v54
	v_fma_f32 v170, -v112, v167, v170
	v_fma_f32 v171, v112, v166, v171
	v_fma_f32 v172, -v114, v169, v172
	v_fma_f32 v173, v114, v168, v173
	v_cvt_pk_bf16_f32 v178, v170, v172
	v_cvt_pk_bf16_f32 v179, v171, v173
	ds_write_b64 v175, v[178:179] offset:1632
	v_fma_f32 v166, v113, v170, v7
	v_fma_f32 v167, v113, v171, v23
	v_fma_f32 v168, v115, v172, v39
	v_fma_f32 v169, v115, v173, v55
	v_fma_f32 v166, -v112, v171, v166
	v_fma_f32 v167, v112, v170, v167
	v_fma_f32 v168, -v114, v173, v168
	v_fma_f32 v169, v114, v172, v169
	v_cvt_pk_bf16_f32 v178, v166, v168
	v_cvt_pk_bf16_f32 v179, v167, v169
	ds_write_b64 v175, v[178:179] offset:1904
	v_fma_f32 v170, v113, v166, v8
	v_fma_f32 v171, v113, v167, v24
	v_fma_f32 v172, v115, v168, v40
	v_fma_f32 v173, v115, v169, v56
	v_fma_f32 v170, -v112, v167, v170
	v_fma_f32 v171, v112, v166, v171
	v_fma_f32 v172, -v114, v169, v172
	v_fma_f32 v173, v114, v168, v173
	v_cvt_pk_bf16_f32 v178, v170, v172
	v_cvt_pk_bf16_f32 v179, v171, v173
	ds_write_b64 v175, v[178:179] offset:2176
	v_fma_f32 v166, v113, v170, v9
	v_fma_f32 v167, v113, v171, v25
	v_fma_f32 v168, v115, v172, v41
	v_fma_f32 v169, v115, v173, v57
	v_fma_f32 v166, -v112, v171, v166
	v_fma_f32 v167, v112, v170, v167
	v_fma_f32 v168, -v114, v173, v168
	v_fma_f32 v169, v114, v172, v169
	v_cvt_pk_bf16_f32 v178, v166, v168
	v_cvt_pk_bf16_f32 v179, v167, v169
	ds_write_b64 v175, v[178:179] offset:2448
	v_fma_f32 v170, v113, v166, v10
	v_fma_f32 v171, v113, v167, v26
	v_fma_f32 v172, v115, v168, v42
	v_fma_f32 v173, v115, v169, v58
	v_fma_f32 v170, -v112, v167, v170
	v_fma_f32 v171, v112, v166, v171
	v_fma_f32 v172, -v114, v169, v172
	v_fma_f32 v173, v114, v168, v173
	v_cvt_pk_bf16_f32 v178, v170, v172
	v_cvt_pk_bf16_f32 v179, v171, v173
	ds_write_b64 v175, v[178:179] offset:2720
	v_fma_f32 v166, v113, v170, v11
	v_fma_f32 v167, v113, v171, v27
	v_fma_f32 v168, v115, v172, v43
	v_fma_f32 v169, v115, v173, v59
	v_fma_f32 v166, -v112, v171, v166
	v_fma_f32 v167, v112, v170, v167
	v_fma_f32 v168, -v114, v173, v168
	v_fma_f32 v169, v114, v172, v169
	v_cvt_pk_bf16_f32 v178, v166, v168
	v_cvt_pk_bf16_f32 v179, v167, v169
	ds_write_b64 v175, v[178:179] offset:2992
	v_fma_f32 v170, v113, v166, v12
	v_fma_f32 v171, v113, v167, v28
	v_fma_f32 v172, v115, v168, v44
	v_fma_f32 v173, v115, v169, v60
	v_fma_f32 v170, -v112, v167, v170
	v_fma_f32 v171, v112, v166, v171
	v_fma_f32 v172, -v114, v169, v172
	v_fma_f32 v173, v114, v168, v173
	v_cvt_pk_bf16_f32 v178, v170, v172
	v_cvt_pk_bf16_f32 v179, v171, v173
	ds_write_b64 v175, v[178:179] offset:3264
	v_fma_f32 v166, v113, v170, v13
	v_fma_f32 v167, v113, v171, v29
	v_fma_f32 v168, v115, v172, v45
	v_fma_f32 v169, v115, v173, v61
	v_fma_f32 v166, -v112, v171, v166
	v_fma_f32 v167, v112, v170, v167
	v_fma_f32 v168, -v114, v173, v168
	v_fma_f32 v169, v114, v172, v169
	v_cvt_pk_bf16_f32 v178, v166, v168
	v_cvt_pk_bf16_f32 v179, v167, v169
	ds_write_b64 v175, v[178:179] offset:3536
	v_fma_f32 v170, v113, v166, v14
	v_fma_f32 v171, v113, v167, v30
	v_fma_f32 v172, v115, v168, v46
	v_fma_f32 v173, v115, v169, v62
	v_fma_f32 v170, -v112, v167, v170
	v_fma_f32 v171, v112, v166, v171
	v_fma_f32 v172, -v114, v169, v172
	v_fma_f32 v173, v114, v168, v173
	v_cvt_pk_bf16_f32 v178, v170, v172
	v_cvt_pk_bf16_f32 v179, v171, v173
	ds_write_b64 v175, v[178:179] offset:3808
	v_fma_f32 v166, v113, v170, v15
	v_fma_f32 v167, v113, v171, v31
	v_fma_f32 v168, v115, v172, v47
	v_fma_f32 v169, v115, v173, v63
	v_fma_f32 v166, -v112, v171, v166
	v_fma_f32 v167, v112, v170, v167
	v_fma_f32 v168, -v114, v173, v168
	v_fma_f32 v169, v114, v172, v169
	v_cvt_pk_bf16_f32 v178, v166, v168
	v_cvt_pk_bf16_f32 v179, v167, v169
	ds_write_b64 v175, v[178:179] offset:4080
	s_waitcnt vmcnt(21)
	v_mfma_f32_32x32x16_bf16 v[0:15], v[132:135], v[64:67], 0
	v_mfma_f32_32x32x16_bf16 v[16:31], v[132:135], v[68:71], 0
	v_mfma_f32_32x32x16_bf16 v[32:47], v[132:135], v[72:75], 0
	v_mfma_f32_32x32x16_bf16 v[48:63], v[132:135], v[76:79], 0
	v_add_u32_e32 v188, 48, v130
	v_ashrrev_i32_e32 v189, 31, v188
	v_lshlrev_b64 v[188:189], 11, v[188:189]
	v_lshl_add_u64 v[188:189], v[118:119], 0, v[188:189]
	global_load_dwordx4 v[132:135], v[188:189], off
	ds_read_b128 v[214:217], v176
	ds_read_b128 v[218:221], v176 offset:64
	ds_read_b128 v[222:225], v176 offset:128
	ds_read_b128 v[226:229], v176 offset:192
	ds_read_b128 v[230:233], v176 offset:4352
	ds_read_b128 v[234:237], v176 offset:4416
	ds_read_b128 v[238:241], v176 offset:4480
	ds_read_b128 v[242:245], v176 offset:4544
	s_waitcnt lgkmcnt(7)
	v_mfma_f32_16x16x32_bf16 v[180:183], v[80:83], v[214:217], 0
	s_waitcnt lgkmcnt(6)
	v_mfma_f32_16x16x32_bf16 v[180:183], v[84:87], v[218:221], v[180:183]
	s_waitcnt lgkmcnt(5)
	v_mfma_f32_16x16x32_bf16 v[180:183], v[88:91], v[222:225], v[180:183]
	s_waitcnt lgkmcnt(4)
	v_mfma_f32_16x16x32_bf16 v[180:183], v[92:95], v[226:229], v[180:183]
	s_waitcnt lgkmcnt(3)
	v_mfma_f32_16x16x32_bf16 v[184:187], v[80:83], v[230:233], 0
	s_waitcnt lgkmcnt(2)
	v_mfma_f32_16x16x32_bf16 v[184:187], v[84:87], v[234:237], v[184:187]
	s_waitcnt lgkmcnt(1)
	v_mfma_f32_16x16x32_bf16 v[184:187], v[88:91], v[238:241], v[184:187]
	s_waitcnt lgkmcnt(0)
	v_mfma_f32_16x16x32_bf16 v[184:187], v[92:95], v[242:245], v[184:187]
	s_waitcnt vmcnt(18)
	v_lshlrev_b32_e32 v246, 16, v144
	v_and_b32_e32 v247, 0xffff0000, v144
	v_lshlrev_b32_e32 v248, 16, v145
	v_and_b32_e32 v249, 0xffff0000, v145
	v_lshlrev_b32_e32 v250, 16, v146
	v_and_b32_e32 v251, 0xffff0000, v146
	v_lshlrev_b32_e32 v252, 16, v147
	v_and_b32_e32 v253, 0xffff0000, v147
	v_add_u32_e32 v202, 32, v191
	v_ashrrev_i32_e32 v203, 31, v202
	v_lshlrev_b64 v[202:203], 11, v[202:203]
	v_lshl_add_u64 v[202:203], v[122:123], 0, v[202:203]
	v_add_u32_e32 v204, 96, v191
	v_ashrrev_i32_e32 v205, 31, v204
	v_lshlrev_b64 v[204:205], 11, v[204:205]
	v_lshl_add_u64 v[204:205], v[122:123], 0, v[204:205]
	v_fma_f32 v180, v96, v246, v180
	v_fma_f32 v181, v97, v247, v181
	v_fma_f32 v182, v98, v248, v182
	v_fma_f32 v183, v99, v249, v183
	v_fma_f32 v184, v96, v250, v184
	v_fma_f32 v185, v97, v251, v185
	v_fma_f32 v186, v98, v252, v186
	v_fma_f32 v187, v99, v253, v187
	v_mul_f32_e32 v214, v180, v180
	v_mul_f32_e32 v215, v181, v181
	v_mul_f32_e32 v216, v182, v182
	v_mul_f32_e32 v217, v183, v183
	v_mul_f32_e32 v218, v184, v184
	v_mul_f32_e32 v219, v185, v185
	v_mul_f32_e32 v220, v186, v186
	v_mul_f32_e32 v221, v187, v187
	v_fma_f32 v214, v214, s101, 1.0
	v_fma_f32 v215, v215, s101, 1.0
	v_fma_f32 v216, v216, s101, 1.0
	v_fma_f32 v217, v217, s101, 1.0
	v_fma_f32 v218, v218, s101, 1.0
	v_fma_f32 v219, v219, s101, 1.0
	v_fma_f32 v220, v220, s101, 1.0
	v_fma_f32 v221, v221, s101, 1.0
	v_mul_f32_e32 v214, v214, v180
	v_mul_f32_e32 v215, v215, v181
	v_mul_f32_e32 v216, v216, v182
	v_mul_f32_e32 v217, v217, v183
	v_mul_f32_e32 v218, v218, v184
	v_mul_f32_e32 v219, v219, v185
	v_mul_f32_e32 v220, v220, v186
	v_mul_f32_e32 v221, v221, v187
	v_mul_f32_e32 v214, 0x40135761, v214
	v_mul_f32_e32 v215, 0x40135761, v215
	v_mul_f32_e32 v216, 0x40135761, v216
	v_mul_f32_e32 v217, 0x40135761, v217
	v_mul_f32_e32 v218, 0x40135761, v218
	v_mul_f32_e32 v219, 0x40135761, v219
	v_mul_f32_e32 v220, 0x40135761, v220
	v_mul_f32_e32 v221, 0x40135761, v221
	v_exp_f32_e32 v214, v214
	v_exp_f32_e32 v215, v215
	v_exp_f32_e32 v216, v216
	v_exp_f32_e32 v217, v217
	v_exp_f32_e32 v218, v218
	v_exp_f32_e32 v219, v219
	v_exp_f32_e32 v220, v220
	v_exp_f32_e32 v221, v221
	v_mul_f32_e32 v222, 0.5, v180
	v_mul_f32_e32 v223, 0.5, v181
	v_mul_f32_e32 v224, 0.5, v182
	v_mul_f32_e32 v225, 0.5, v183
	v_mul_f32_e32 v226, 0.5, v184
	v_mul_f32_e32 v227, 0.5, v185
	v_mul_f32_e32 v228, 0.5, v186
	v_mul_f32_e32 v229, 0.5, v187
	v_add_f32_e32 v214, 1.0, v214
	v_add_f32_e32 v215, 1.0, v215
	v_add_f32_e32 v216, 1.0, v216
	v_add_f32_e32 v217, 1.0, v217
	v_add_f32_e32 v218, 1.0, v218
	v_add_f32_e32 v219, 1.0, v219
	v_add_f32_e32 v220, 1.0, v220
	v_add_f32_e32 v221, 1.0, v221
	v_rcp_f32_e32 v214, v214
	v_rcp_f32_e32 v215, v215
	v_rcp_f32_e32 v216, v216
	v_rcp_f32_e32 v217, v217
	v_rcp_f32_e32 v218, v218
	v_rcp_f32_e32 v219, v219
	v_rcp_f32_e32 v220, v220
	v_rcp_f32_e32 v221, v221
	s_nop 0
	v_fma_f32 v214, v214, -2.0, 1.0
	v_fma_f32 v215, v215, -2.0, 1.0
	v_fma_f32 v216, v216, -2.0, 1.0
	v_fma_f32 v217, v217, -2.0, 1.0
	v_fma_f32 v218, v218, -2.0, 1.0
	v_fma_f32 v219, v219, -2.0, 1.0
	v_fma_f32 v220, v220, -2.0, 1.0
	v_fma_f32 v221, v221, -2.0, 1.0
	v_fma_f32 v180, v222, v214, v222
	v_fma_f32 v181, v223, v215, v223
	v_fma_f32 v182, v224, v216, v224
	v_fma_f32 v183, v225, v217, v225
	v_fma_f32 v184, v226, v218, v226
	v_fma_f32 v185, v227, v219, v227
	v_fma_f32 v186, v228, v220, v228
	v_fma_f32 v187, v229, v221, v229
	v_cvt_pk_bf16_f32 v214, v180, v181
	v_cvt_pk_bf16_f32 v215, v182, v183
	v_cvt_pk_bf16_f32 v216, v184, v185
	v_cvt_pk_bf16_f32 v217, v186, v187
	global_store_dwordx2 v[202:203], v[214:215], off
	global_store_dwordx2 v[204:205], v[216:217], off
	v_add_u32_e32 v188, 32, v131
	v_ashrrev_i32_e32 v189, 31, v188
	v_lshlrev_b64 v[188:189], 11, v[188:189]
	v_lshl_add_u64 v[188:189], v[120:121], 0, v[188:189]
	global_load_dwordx2 v[144:145], v[188:189], off
	v_add_u32_e32 v188, 96, v131
	v_ashrrev_i32_e32 v189, 31, v188
	v_lshlrev_b64 v[188:189], 11, v[188:189]
	v_lshl_add_u64 v[188:189], v[120:121], 0, v[188:189]
	global_load_dwordx2 v[146:147], v[188:189], off
	v_fma_f32 v170, v113, v166, v0
	v_fma_f32 v171, v113, v167, v16
	v_fma_f32 v172, v115, v168, v32
	v_fma_f32 v173, v115, v169, v48
	v_fma_f32 v170, -v112, v167, v170
	v_fma_f32 v171, v112, v166, v171
	v_fma_f32 v172, -v114, v169, v172
	v_fma_f32 v173, v114, v168, v173
	v_cvt_pk_bf16_f32 v178, v170, v172
	v_cvt_pk_bf16_f32 v179, v171, v173
	ds_write_b64 v175, v[178:179]
	v_fma_f32 v166, v113, v170, v1
	v_fma_f32 v167, v113, v171, v17
	v_fma_f32 v168, v115, v172, v33
	v_fma_f32 v169, v115, v173, v49
	v_fma_f32 v166, -v112, v171, v166
	v_fma_f32 v167, v112, v170, v167
	v_fma_f32 v168, -v114, v173, v168
	v_fma_f32 v169, v114, v172, v169
	v_cvt_pk_bf16_f32 v178, v166, v168
	v_cvt_pk_bf16_f32 v179, v167, v169
	ds_write_b64 v175, v[178:179] offset:272
	v_fma_f32 v170, v113, v166, v2
	v_fma_f32 v171, v113, v167, v18
	v_fma_f32 v172, v115, v168, v34
	v_fma_f32 v173, v115, v169, v50
	v_fma_f32 v170, -v112, v167, v170
	v_fma_f32 v171, v112, v166, v171
	v_fma_f32 v172, -v114, v169, v172
	v_fma_f32 v173, v114, v168, v173
	v_cvt_pk_bf16_f32 v178, v170, v172
	v_cvt_pk_bf16_f32 v179, v171, v173
	ds_write_b64 v175, v[178:179] offset:544
	v_fma_f32 v166, v113, v170, v3
	v_fma_f32 v167, v113, v171, v19
	v_fma_f32 v168, v115, v172, v35
	v_fma_f32 v169, v115, v173, v51
	v_fma_f32 v166, -v112, v171, v166
	v_fma_f32 v167, v112, v170, v167
	v_fma_f32 v168, -v114, v173, v168
	v_fma_f32 v169, v114, v172, v169
	v_cvt_pk_bf16_f32 v178, v166, v168
	v_cvt_pk_bf16_f32 v179, v167, v169
	ds_write_b64 v175, v[178:179] offset:816
	v_fma_f32 v170, v113, v166, v4
	v_fma_f32 v171, v113, v167, v20
	v_fma_f32 v172, v115, v168, v36
	v_fma_f32 v173, v115, v169, v52
	v_fma_f32 v170, -v112, v167, v170
	v_fma_f32 v171, v112, v166, v171
	v_fma_f32 v172, -v114, v169, v172
	v_fma_f32 v173, v114, v168, v173
	v_cvt_pk_bf16_f32 v178, v170, v172
	v_cvt_pk_bf16_f32 v179, v171, v173
	ds_write_b64 v175, v[178:179] offset:1088
	v_fma_f32 v166, v113, v170, v5
	v_fma_f32 v167, v113, v171, v21
	v_fma_f32 v168, v115, v172, v37
	v_fma_f32 v169, v115, v173, v53
	v_fma_f32 v166, -v112, v171, v166
	v_fma_f32 v167, v112, v170, v167
	v_fma_f32 v168, -v114, v173, v168
	v_fma_f32 v169, v114, v172, v169
	v_cvt_pk_bf16_f32 v178, v166, v168
	v_cvt_pk_bf16_f32 v179, v167, v169
	ds_write_b64 v175, v[178:179] offset:1360
	v_fma_f32 v170, v113, v166, v6
	v_fma_f32 v171, v113, v167, v22
	v_fma_f32 v172, v115, v168, v38
	v_fma_f32 v173, v115, v169, v54
	v_fma_f32 v170, -v112, v167, v170
	v_fma_f32 v171, v112, v166, v171
	v_fma_f32 v172, -v114, v169, v172
	v_fma_f32 v173, v114, v168, v173
	v_cvt_pk_bf16_f32 v178, v170, v172
	v_cvt_pk_bf16_f32 v179, v171, v173
	ds_write_b64 v175, v[178:179] offset:1632
	v_fma_f32 v166, v113, v170, v7
	v_fma_f32 v167, v113, v171, v23
	v_fma_f32 v168, v115, v172, v39
	v_fma_f32 v169, v115, v173, v55
	v_fma_f32 v166, -v112, v171, v166
	v_fma_f32 v167, v112, v170, v167
	v_fma_f32 v168, -v114, v173, v168
	v_fma_f32 v169, v114, v172, v169
	v_cvt_pk_bf16_f32 v178, v166, v168
	v_cvt_pk_bf16_f32 v179, v167, v169
	ds_write_b64 v175, v[178:179] offset:1904
	v_fma_f32 v170, v113, v166, v8
	v_fma_f32 v171, v113, v167, v24
	v_fma_f32 v172, v115, v168, v40
	v_fma_f32 v173, v115, v169, v56
	v_fma_f32 v170, -v112, v167, v170
	v_fma_f32 v171, v112, v166, v171
	v_fma_f32 v172, -v114, v169, v172
	v_fma_f32 v173, v114, v168, v173
	v_cvt_pk_bf16_f32 v178, v170, v172
	v_cvt_pk_bf16_f32 v179, v171, v173
	ds_write_b64 v175, v[178:179] offset:2176
	v_fma_f32 v166, v113, v170, v9
	v_fma_f32 v167, v113, v171, v25
	v_fma_f32 v168, v115, v172, v41
	v_fma_f32 v169, v115, v173, v57
	v_fma_f32 v166, -v112, v171, v166
	v_fma_f32 v167, v112, v170, v167
	v_fma_f32 v168, -v114, v173, v168
	v_fma_f32 v169, v114, v172, v169
	v_cvt_pk_bf16_f32 v178, v166, v168
	v_cvt_pk_bf16_f32 v179, v167, v169
	ds_write_b64 v175, v[178:179] offset:2448
	v_fma_f32 v170, v113, v166, v10
	v_fma_f32 v171, v113, v167, v26
	v_fma_f32 v172, v115, v168, v42
	v_fma_f32 v173, v115, v169, v58
	v_fma_f32 v170, -v112, v167, v170
	v_fma_f32 v171, v112, v166, v171
	v_fma_f32 v172, -v114, v169, v172
	v_fma_f32 v173, v114, v168, v173
	v_cvt_pk_bf16_f32 v178, v170, v172
	v_cvt_pk_bf16_f32 v179, v171, v173
	ds_write_b64 v175, v[178:179] offset:2720
	v_fma_f32 v166, v113, v170, v11
	v_fma_f32 v167, v113, v171, v27
	v_fma_f32 v168, v115, v172, v43
	v_fma_f32 v169, v115, v173, v59
	v_fma_f32 v166, -v112, v171, v166
	v_fma_f32 v167, v112, v170, v167
	v_fma_f32 v168, -v114, v173, v168
	v_fma_f32 v169, v114, v172, v169
	v_cvt_pk_bf16_f32 v178, v166, v168
	v_cvt_pk_bf16_f32 v179, v167, v169
	ds_write_b64 v175, v[178:179] offset:2992
	v_fma_f32 v170, v113, v166, v12
	v_fma_f32 v171, v113, v167, v28
	v_fma_f32 v172, v115, v168, v44
	v_fma_f32 v173, v115, v169, v60
	v_fma_f32 v170, -v112, v167, v170
	v_fma_f32 v171, v112, v166, v171
	v_fma_f32 v172, -v114, v169, v172
	v_fma_f32 v173, v114, v168, v173
	v_cvt_pk_bf16_f32 v178, v170, v172
	v_cvt_pk_bf16_f32 v179, v171, v173
	ds_write_b64 v175, v[178:179] offset:3264
	v_fma_f32 v166, v113, v170, v13
	v_fma_f32 v167, v113, v171, v29
	v_fma_f32 v168, v115, v172, v45
	v_fma_f32 v169, v115, v173, v61
	v_fma_f32 v166, -v112, v171, v166
	v_fma_f32 v167, v112, v170, v167
	v_fma_f32 v168, -v114, v173, v168
	v_fma_f32 v169, v114, v172, v169
	v_cvt_pk_bf16_f32 v178, v166, v168
	v_cvt_pk_bf16_f32 v179, v167, v169
	ds_write_b64 v175, v[178:179] offset:3536
	v_fma_f32 v170, v113, v166, v14
	v_fma_f32 v171, v113, v167, v30
	v_fma_f32 v172, v115, v168, v46
	v_fma_f32 v173, v115, v169, v62
	v_fma_f32 v170, -v112, v167, v170
	v_fma_f32 v171, v112, v166, v171
	v_fma_f32 v172, -v114, v169, v172
	v_fma_f32 v173, v114, v168, v173
	v_cvt_pk_bf16_f32 v178, v170, v172
	v_cvt_pk_bf16_f32 v179, v171, v173
	ds_write_b64 v175, v[178:179] offset:3808
	v_fma_f32 v166, v113, v170, v15
	v_fma_f32 v167, v113, v171, v31
	v_fma_f32 v168, v115, v172, v47
	v_fma_f32 v169, v115, v173, v63
	v_fma_f32 v166, -v112, v171, v166
	v_fma_f32 v167, v112, v170, v167
	v_fma_f32 v168, -v114, v173, v168
	v_fma_f32 v169, v114, v172, v169
	v_cvt_pk_bf16_f32 v178, v166, v168
	v_cvt_pk_bf16_f32 v179, v167, v169
	ds_write_b64 v175, v[178:179] offset:4080
	ds_read_b128 v[214:217], v176
	ds_read_b128 v[218:221], v176 offset:64
	ds_read_b128 v[222:225], v176 offset:128
	ds_read_b128 v[226:229], v176 offset:192
	ds_read_b128 v[230:233], v176 offset:4352
	ds_read_b128 v[234:237], v176 offset:4416
	ds_read_b128 v[238:241], v176 offset:4480
	ds_read_b128 v[242:245], v176 offset:4544
	s_waitcnt lgkmcnt(7)
	v_mfma_f32_16x16x32_bf16 v[180:183], v[80:83], v[214:217], 0
	s_waitcnt lgkmcnt(6)
	v_mfma_f32_16x16x32_bf16 v[180:183], v[84:87], v[218:221], v[180:183]
	s_waitcnt lgkmcnt(5)
	v_mfma_f32_16x16x32_bf16 v[180:183], v[88:91], v[222:225], v[180:183]
	s_waitcnt lgkmcnt(4)
	v_mfma_f32_16x16x32_bf16 v[180:183], v[92:95], v[226:229], v[180:183]
	s_waitcnt lgkmcnt(3)
	v_mfma_f32_16x16x32_bf16 v[184:187], v[80:83], v[230:233], 0
	s_waitcnt lgkmcnt(2)
	v_mfma_f32_16x16x32_bf16 v[184:187], v[84:87], v[234:237], v[184:187]
	s_waitcnt lgkmcnt(1)
	v_mfma_f32_16x16x32_bf16 v[184:187], v[88:91], v[238:241], v[184:187]
	s_waitcnt lgkmcnt(0)
	v_mfma_f32_16x16x32_bf16 v[184:187], v[92:95], v[242:245], v[184:187]
	s_waitcnt vmcnt(18)
	v_lshlrev_b32_e32 v246, 16, v148
	v_and_b32_e32 v247, 0xffff0000, v148
	v_lshlrev_b32_e32 v248, 16, v149
	v_and_b32_e32 v249, 0xffff0000, v149
	v_lshlrev_b32_e32 v250, 16, v150
	v_and_b32_e32 v251, 0xffff0000, v150
	v_lshlrev_b32_e32 v252, 16, v151
	v_and_b32_e32 v253, 0xffff0000, v151
	v_add_u32_e32 v202, 48, v191
	v_ashrrev_i32_e32 v203, 31, v202
	v_lshlrev_b64 v[202:203], 11, v[202:203]
	v_lshl_add_u64 v[202:203], v[122:123], 0, v[202:203]
	v_add_u32_e32 v204, 112, v191
	v_ashrrev_i32_e32 v205, 31, v204
	v_lshlrev_b64 v[204:205], 11, v[204:205]
	v_lshl_add_u64 v[204:205], v[122:123], 0, v[204:205]
	v_fma_f32 v180, v96, v246, v180
	v_fma_f32 v181, v97, v247, v181
	v_fma_f32 v182, v98, v248, v182
	v_fma_f32 v183, v99, v249, v183
	v_fma_f32 v184, v96, v250, v184
	v_fma_f32 v185, v97, v251, v185
	v_fma_f32 v186, v98, v252, v186
	v_fma_f32 v187, v99, v253, v187
	v_mul_f32_e32 v214, v180, v180
	v_mul_f32_e32 v215, v181, v181
	v_mul_f32_e32 v216, v182, v182
	v_mul_f32_e32 v217, v183, v183
	v_mul_f32_e32 v218, v184, v184
	v_mul_f32_e32 v219, v185, v185
	v_mul_f32_e32 v220, v186, v186
	v_mul_f32_e32 v221, v187, v187
	v_fma_f32 v214, v214, s101, 1.0
	v_fma_f32 v215, v215, s101, 1.0
	v_fma_f32 v216, v216, s101, 1.0
	v_fma_f32 v217, v217, s101, 1.0
	v_fma_f32 v218, v218, s101, 1.0
	v_fma_f32 v219, v219, s101, 1.0
	v_fma_f32 v220, v220, s101, 1.0
	v_fma_f32 v221, v221, s101, 1.0
	v_mul_f32_e32 v214, v214, v180
	v_mul_f32_e32 v215, v215, v181
	v_mul_f32_e32 v216, v216, v182
	v_mul_f32_e32 v217, v217, v183
	v_mul_f32_e32 v218, v218, v184
	v_mul_f32_e32 v219, v219, v185
	v_mul_f32_e32 v220, v220, v186
	v_mul_f32_e32 v221, v221, v187
	v_mul_f32_e32 v214, 0x40135761, v214
	v_mul_f32_e32 v215, 0x40135761, v215
	v_mul_f32_e32 v216, 0x40135761, v216
	v_mul_f32_e32 v217, 0x40135761, v217
	v_mul_f32_e32 v218, 0x40135761, v218
	v_mul_f32_e32 v219, 0x40135761, v219
	v_mul_f32_e32 v220, 0x40135761, v220
	v_mul_f32_e32 v221, 0x40135761, v221
	v_exp_f32_e32 v214, v214
	v_exp_f32_e32 v215, v215
	v_exp_f32_e32 v216, v216
	v_exp_f32_e32 v217, v217
	v_exp_f32_e32 v218, v218
	v_exp_f32_e32 v219, v219
	v_exp_f32_e32 v220, v220
	v_exp_f32_e32 v221, v221
	v_mul_f32_e32 v222, 0.5, v180
	v_mul_f32_e32 v223, 0.5, v181
	v_mul_f32_e32 v224, 0.5, v182
	v_mul_f32_e32 v225, 0.5, v183
	v_mul_f32_e32 v226, 0.5, v184
	v_mul_f32_e32 v227, 0.5, v185
	v_mul_f32_e32 v228, 0.5, v186
	v_mul_f32_e32 v229, 0.5, v187
	v_add_f32_e32 v214, 1.0, v214
	v_add_f32_e32 v215, 1.0, v215
	v_add_f32_e32 v216, 1.0, v216
	v_add_f32_e32 v217, 1.0, v217
	v_add_f32_e32 v218, 1.0, v218
	v_add_f32_e32 v219, 1.0, v219
	v_add_f32_e32 v220, 1.0, v220
	v_add_f32_e32 v221, 1.0, v221
	v_rcp_f32_e32 v214, v214
	v_rcp_f32_e32 v215, v215
	v_rcp_f32_e32 v216, v216
	v_rcp_f32_e32 v217, v217
	v_rcp_f32_e32 v218, v218
	v_rcp_f32_e32 v219, v219
	v_rcp_f32_e32 v220, v220
	v_rcp_f32_e32 v221, v221
	s_nop 0
	v_fma_f32 v214, v214, -2.0, 1.0
	v_fma_f32 v215, v215, -2.0, 1.0
	v_fma_f32 v216, v216, -2.0, 1.0
	v_fma_f32 v217, v217, -2.0, 1.0
	v_fma_f32 v218, v218, -2.0, 1.0
	v_fma_f32 v219, v219, -2.0, 1.0
	v_fma_f32 v220, v220, -2.0, 1.0
	v_fma_f32 v221, v221, -2.0, 1.0
	v_fma_f32 v180, v222, v214, v222
	v_fma_f32 v181, v223, v215, v223
	v_fma_f32 v182, v224, v216, v224
	v_fma_f32 v183, v225, v217, v225
	v_fma_f32 v184, v226, v218, v226
	v_fma_f32 v185, v227, v219, v227
	v_fma_f32 v186, v228, v220, v228
	v_fma_f32 v187, v229, v221, v229
	v_cvt_pk_bf16_f32 v214, v180, v181
	v_cvt_pk_bf16_f32 v215, v182, v183
	v_cvt_pk_bf16_f32 v216, v184, v185
	v_cvt_pk_bf16_f32 v217, v186, v187
	global_store_dwordx2 v[202:203], v[214:215], off
	global_store_dwordx2 v[204:205], v[216:217], off
	v_add_u32_e32 v188, 48, v131
	v_ashrrev_i32_e32 v189, 31, v188
	v_lshlrev_b64 v[188:189], 11, v[188:189]
	v_lshl_add_u64 v[188:189], v[120:121], 0, v[188:189]
	global_load_dwordx2 v[148:149], v[188:189], off
	v_add_u32_e32 v188, 112, v131
	v_ashrrev_i32_e32 v189, 31, v188
	v_lshlrev_b64 v[188:189], 11, v[188:189]
	v_lshl_add_u64 v[188:189], v[120:121], 0, v[188:189]
	global_load_dwordx2 v[150:151], v[188:189], off
	v_mov_b32_e32 v190, v130
	v_mov_b32_e32 v191, v131
	v_mov_b32_e32 v128, v177
	s_andn2_b64 exec, exec, s[8:9]
	s_cbranch_execnz .LBB0_95
